# s1 = r1 + sum-of-squares lane reductions in the Z dss and final-residual epilogues via v_permlane16/32_swap instead of ds_bpermute + shfl address math (bit-identical)
# baseline (speedup 1.0000x reference)
; __device__ __forceinline__ void unpack8(const u32x4 w, float (&f)[8]) { f[0] = bf_lo(w.x); f[1] = bf_hi(w.x); f[2] = bf_lo(w.y); f[3] = bf_hi(w.y); f[4] = bf_lo(w.z); f[5] = bf_hi(w.z); f[6] = bf_lo(w.w); f[7] = bf_hi(w.w); }
;     __device__ __forceinline__ void operator()(f32x4 (&acc)[2][2][4][2], const Unit& u, int wr, int wc, int fr, int fq) const {
;     ...
;         const int row0 = u.pm * BM + wr * 64 + fr, col0 = u.pn * BM + wc * 32 + 8 * fq, wv = 4 * wr + wc;
;         u32x4 xo[2][4][2];
; #pragma unroll
;         for (int ai = 0; ai < 2; ++ai)
; #pragma unroll
;             for (int m = 0; m < 4; ++m) { const size_t off = (size_t)(row0 + ai * HALF + m * 16) * D + col0;
; #pragma unroll
;                 for (int bj = 0; bj < 2; ++bj) xo[ai][m][bj] = *(const u32x4*)(xb + off + bj * HALF); }
; #pragma unroll
;         for (int ai = 0; ai < 2; ++ai)
; #pragma unroll
;             for (int m = 0; m < 4; ++m) { const int row = row0 + ai * HALF + m * 16; float sq = 0.f;
; #pragma unroll
;                 for (int bj = 0; bj < 2; ++bj) {
;                     float xf[8]; unpack8(xo[ai][m][bj], xf);
;                     const f32x4 x0 = (f32x4){xf[0], xf[1], xf[2], xf[3]} + acc[ai][bj][m][0], x1 = (f32x4){xf[4], xf[5], xf[6], xf[7]} + acc[ai][bj][m][1];
;                     sq += (x0[0] * x0[0] + x0[1] * x0[1]) + (x0[2] * x0[2] + x0[3] * x0[3]) + (x1[0] * x1[0] + x1[1] * x1[1]) + (x1[2] * x1[2] + x1[3] * x1[3]);
;                     acc[ai][bj][m][0] = x0; acc[ai][bj][m][1] = x1; }
;                 sq += __shfl_xor(sq, 16); sq += __shfl_xor(sq, 32);
;                 if (fq == 0) __hip_atomic_store(ssn + (size_t)row * 16 + u.pn * 4 + wc, sq, __ATOMIC_RELAXED, __HIP_MEMORY_SCOPE_AGENT); }
.LBB0_351:
	s_lshl_b32 s38, s34, 8
	v_mbcnt_lo_u32_b32 v195, -1, 0
	v_mbcnt_hi_u32_b32 v195, -1, v195
	s_add_i32 s0, s38, s54
	v_and_b32_e32 v194, 15, v195
	v_or_b32_e32 v232, s0, v194
	s_lshl_b32 s0, s35, 8
	v_ashrrev_i32_e32 v130, 1, v195
	s_or_b32 s0, s0, s55
	v_and_b32_e32 v130, -8, v130
	v_add_u32_e32 v212, s0, v130
	v_readlane_b32 s0, v254, 57
	v_ashrrev_i32_e32 v213, 31, v212
	v_readlane_b32 s1, v254, 58
	v_ashrrev_i32_e32 v233, 31, v232
	v_lshlrev_b64 v[130:131], 11, v[232:233]
	v_lshl_add_u64 v[138:139], v[212:213], 1, s[0:1]
	v_lshl_add_u64 v[130:131], v[138:139], 0, v[130:131]
	global_load_dwordx4 v[190:193], v[130:131], off
	global_load_dwordx4 v[186:189], v[130:131], off offset:256
	v_or_b32_e32 v230, 16, v232
	v_ashrrev_i32_e32 v231, 31, v230
	v_lshlrev_b64 v[130:131], 11, v[230:231]
	v_or_b32_e32 v228, 32, v232
	v_lshl_add_u64 v[130:131], v[138:139], 0, v[130:131]
	v_ashrrev_i32_e32 v229, 31, v228
	global_load_dwordx4 v[182:185], v[130:131], off
	global_load_dwordx4 v[178:181], v[130:131], off offset:256
	v_lshlrev_b64 v[130:131], 11, v[228:229]
	v_or_b32_e32 v226, 48, v232
	v_lshl_add_u64 v[130:131], v[138:139], 0, v[130:131]
	v_ashrrev_i32_e32 v227, 31, v226
	global_load_dwordx4 v[174:177], v[130:131], off
	global_load_dwordx4 v[170:173], v[130:131], off offset:256
	v_lshlrev_b64 v[130:131], 11, v[226:227]
	v_add_u32_e32 v224, 0x80, v232
	v_lshl_add_u64 v[130:131], v[138:139], 0, v[130:131]
	v_ashrrev_i32_e32 v225, 31, v224
	global_load_dwordx4 v[166:169], v[130:131], off
	global_load_dwordx4 v[162:165], v[130:131], off offset:256
	v_lshlrev_b64 v[130:131], 11, v[224:225]
	v_add_u32_e32 v222, 0x90, v232
	v_lshl_add_u64 v[130:131], v[138:139], 0, v[130:131]
	v_ashrrev_i32_e32 v223, 31, v222
	global_load_dwordx4 v[158:161], v[130:131], off
	global_load_dwordx4 v[154:157], v[130:131], off offset:256
	v_lshlrev_b64 v[130:131], 11, v[222:223]
	v_add_u32_e32 v220, 0xa0, v232
	v_add_u32_e32 v218, 0xb0, v232
	v_lshl_add_u64 v[130:131], v[138:139], 0, v[130:131]
	v_ashrrev_i32_e32 v221, 31, v220
	v_ashrrev_i32_e32 v219, 31, v218
	global_load_dwordx4 v[150:153], v[130:131], off
	global_load_dwordx4 v[142:145], v[130:131], off offset:256
	v_lshlrev_b64 v[130:131], 11, v[220:221]
	v_lshlrev_b64 v[140:141], 11, v[218:219]
	v_lshl_add_u64 v[130:131], v[138:139], 0, v[130:131]
	v_lshl_add_u64 v[138:139], v[138:139], 0, v[140:141]
	global_load_dwordx4 v[134:137], v[130:131], off
	s_nop 0
	global_load_dwordx4 v[130:133], v[130:131], off offset:256
	s_nop 0
	global_load_dwordx4 v[146:149], v[138:139], off
	s_nop 0
	global_load_dwordx4 v[138:141], v[138:139], off offset:256
	v_and_b32_e32 v197, 64, v250
	v_xor_b32_e32 v196, 16, v250
	v_add_u32_e32 v197, 64, v197
	v_cmp_lt_i32_e32 vcc, v196, v197
	s_lshl_b32 s36, s35, 2
	s_ashr_i32 s37, s36, 31
	v_cndmask_b32_e32 v196, v250, v196, vcc
	v_lshlrev_b32_e32 v236, 2, v196
	v_xor_b32_e32 v196, 32, v250
	v_cmp_lt_i32_e32 vcc, v196, v197
	s_waitcnt vmcnt(0) lgkmcnt(0)
	v_lshlrev_b32_e32 v214, 16, v190
	v_and_b32_e32 v215, 0xffff0000, v190
	v_lshlrev_b32_e32 v190, 16, v191
	v_and_b32_e32 v191, 0xffff0000, v191
	v_lshlrev_b32_e32 v216, 16, v192
	v_and_b32_e32 v217, 0xffff0000, v192
	v_lshlrev_b32_e32 v238, 16, v193
	v_and_b32_e32 v239, 0xffff0000, v193
	v_pk_add_f32 v[190:191], v[124:125], v[190:191]
	v_pk_add_f32 v[192:193], v[122:123], v[214:215]
	v_pk_add_f32 v[124:125], v[126:127], v[216:217]
	v_mul_f32_e32 v126, v193, v193
	v_mul_f32_e32 v127, v191, v191
	v_fmac_f32_e32 v126, v192, v192
	v_fmac_f32_e32 v127, v190, v190
	v_add_f32_e32 v126, v126, v127
	v_mul_f32_e32 v127, v125, v125
	v_pk_add_f32 v[122:123], v[128:129], v[238:239]
	v_fmac_f32_e32 v127, v124, v124
	v_add_f32_e32 v126, v127, v126
	v_mul_f32_e32 v127, v123, v123
	v_cndmask_b32_e32 v196, v250, v196, vcc
	v_fmac_f32_e32 v127, v122, v122
	v_lshlrev_b32_e32 v237, 2, v196
	v_add_f32_e32 v196, v127, v126
	v_lshlrev_b32_e32 v126, 16, v186
	v_and_b32_e32 v127, 0xffff0000, v186
	v_lshlrev_b32_e32 v128, 16, v187
	v_and_b32_e32 v129, 0xffff0000, v187
	v_lshlrev_b32_e32 v216, 16, v188
	v_and_b32_e32 v217, 0xffff0000, v188
	v_pk_add_f32 v[186:187], v[120:121], v[128:129]
	v_pk_add_f32 v[214:215], v[118:119], v[126:127]
	v_pk_add_f32 v[216:217], v[114:115], v[216:217]
	v_mul_f32_e32 v114, v215, v215
	v_mul_f32_e32 v115, v187, v187
	v_fmac_f32_e32 v114, v214, v214
	v_fmac_f32_e32 v115, v186, v186
	v_lshlrev_b32_e32 v188, 16, v189
	v_and_b32_e32 v189, 0xffff0000, v189
	v_add_f32_e32 v114, v114, v115
	v_mul_f32_e32 v115, v217, v217
	v_pk_add_f32 v[188:189], v[116:117], v[188:189]
	v_fmac_f32_e32 v115, v216, v216
	v_add_f32_e32 v114, v115, v114
	v_mul_f32_e32 v115, v189, v189
	v_fmac_f32_e32 v115, v188, v188
	v_add_f32_e32 v114, v115, v114
	v_add_f32_e32 v114, v196, v114
	v_mov_b32_e32 v115, v114
	s_nop 1
	v_permlane16_swap_b32_e32 v114, v115
	v_cmp_gt_u32_e32 vcc, 16, v195
	s_waitcnt lgkmcnt(0)
	v_add_f32_e32 v114, v114, v115
	v_mov_b32_e32 v115, v114
	s_nop 1
	v_permlane32_swap_b32_e32 v114, v115
	s_and_saveexec_b64 s[0:1], vcc
	s_cbranch_execz .LBB0_353
	s_waitcnt lgkmcnt(0)
	v_add_f32_e32 v116, v114, v115
	v_lshlrev_b64 v[114:115], 6, v[232:233]
	v_lshl_add_u64 v[114:115], s[22:23], 0, v[114:115]
	v_lshl_add_u64 v[114:115], s[36:37], 2, v[114:115]
	s_lshl_b32 s92, s52, 2
	v_lshl_add_u64 v[114:115], v[114:115], 0, s[92:93]
	global_store_dword v[114:115], v116, off sc1
; __device__ __forceinline__ void unpack8(const u32x4 w, float (&f)[8]) { f[0] = bf_lo(w.x); f[1] = bf_hi(w.x); f[2] = bf_lo(w.y); f[3] = bf_hi(w.y); f[4] = bf_lo(w.z); f[5] = bf_hi(w.z); f[6] = bf_lo(w.w); f[7] = bf_hi(w.w); }
;     __device__ __forceinline__ void operator()(f32x4 (&acc)[2][2][4][2], const Unit& u, int wr, int wc, int fr, int fq) const {
;     ...
;             for (int m = 0; m < 4; ++m) { const int row = row0 + ai * HALF + m * 16; float sq = 0.f;
; #pragma unroll
;                 for (int bj = 0; bj < 2; ++bj) {
;                     float xf[8]; unpack8(xo[ai][m][bj], xf);
;                     const f32x4 x0 = (f32x4){xf[0], xf[1], xf[2], xf[3]} + acc[ai][bj][m][0], x1 = (f32x4){xf[4], xf[5], xf[6], xf[7]} + acc[ai][bj][m][1];
;                     sq += (x0[0] * x0[0] + x0[1] * x0[1]) + (x0[2] * x0[2] + x0[3] * x0[3]) + (x1[0] * x1[0] + x1[1] * x1[1]) + (x1[2] * x1[2] + x1[3] * x1[3]);
;                     acc[ai][bj][m][0] = x0; acc[ai][bj][m][1] = x1; }
;                 sq += __shfl_xor(sq, 16); sq += __shfl_xor(sq, 32);
;                 if (fq == 0) __hip_atomic_store(ssn + (size_t)row * 16 + u.pn * 4 + wc, sq, __ATOMIC_RELAXED, __HIP_MEMORY_SCOPE_AGENT); }
.LBB0_353:
	s_or_b64 exec, exec, s[0:1]
	v_lshlrev_b32_e32 v116, 16, v182
	v_and_b32_e32 v117, 0xffff0000, v182
	v_lshlrev_b32_e32 v114, 16, v183
	s_waitcnt lgkmcnt(0)
	v_and_b32_e32 v115, 0xffff0000, v183
	v_lshlrev_b32_e32 v120, 16, v184
	v_and_b32_e32 v121, 0xffff0000, v184
	v_pk_add_f32 v[114:115], v[112:113], v[114:115]
	v_pk_add_f32 v[118:119], v[110:111], v[116:117]
	v_pk_add_f32 v[120:121], v[106:107], v[120:121]
	v_mul_f32_e32 v106, v119, v119
	v_mul_f32_e32 v107, v115, v115
	v_fmac_f32_e32 v106, v118, v118
	v_fmac_f32_e32 v107, v114, v114
	v_lshlrev_b32_e32 v126, 16, v185
	v_and_b32_e32 v127, 0xffff0000, v185
	v_add_f32_e32 v106, v106, v107
	v_mul_f32_e32 v107, v121, v121
	v_pk_add_f32 v[116:117], v[108:109], v[126:127]
	v_fmac_f32_e32 v107, v120, v120
	v_add_f32_e32 v106, v107, v106
	v_mul_f32_e32 v107, v117, v117
	v_fmac_f32_e32 v107, v116, v116
	v_add_f32_e32 v182, v107, v106
	v_lshlrev_b32_e32 v106, 16, v178
	v_and_b32_e32 v107, 0xffff0000, v178
	v_lshlrev_b32_e32 v108, 16, v179
	v_and_b32_e32 v109, 0xffff0000, v179
	v_lshlrev_b32_e32 v110, 16, v180
	v_and_b32_e32 v111, 0xffff0000, v180
	v_pk_add_f32 v[126:127], v[104:105], v[108:109]
	v_pk_add_f32 v[178:179], v[102:103], v[106:107]
	v_lshlrev_b32_e32 v112, 16, v181
	v_and_b32_e32 v113, 0xffff0000, v181
	v_pk_add_f32 v[180:181], v[98:99], v[110:111]
	v_mul_f32_e32 v98, v179, v179
	v_mul_f32_e32 v99, v127, v127
	v_fmac_f32_e32 v98, v178, v178
	v_fmac_f32_e32 v99, v126, v126
	v_add_f32_e32 v98, v98, v99
	v_mul_f32_e32 v99, v181, v181
	v_pk_add_f32 v[128:129], v[100:101], v[112:113]
	v_fmac_f32_e32 v99, v180, v180
	v_add_f32_e32 v98, v99, v98
	v_mul_f32_e32 v99, v129, v129
	v_fmac_f32_e32 v99, v128, v128
	v_add_f32_e32 v98, v99, v98
	v_add_f32_e32 v98, v182, v98
	v_mov_b32_e32 v99, v98
	s_nop 1
	v_permlane16_swap_b32_e32 v98, v99
	s_waitcnt lgkmcnt(0)
	v_add_f32_e32 v98, v98, v99
	v_mov_b32_e32 v99, v98
	s_nop 1
	v_permlane32_swap_b32_e32 v98, v99
	s_and_saveexec_b64 s[0:1], vcc
	s_cbranch_execz .LBB0_355
	s_waitcnt lgkmcnt(0)
	v_add_f32_e32 v100, v98, v99
	v_lshlrev_b64 v[98:99], 6, v[230:231]
	v_lshl_add_u64 v[98:99], s[22:23], 0, v[98:99]
	v_lshl_add_u64 v[98:99], s[36:37], 2, v[98:99]
	s_lshl_b32 s92, s52, 2
	v_lshl_add_u64 v[98:99], v[98:99], 0, s[92:93]
	global_store_dword v[98:99], v100, off sc1
.LBB0_355:
	s_or_b64 exec, exec, s[0:1]
	v_lshlrev_b32_e32 v100, 16, v174
	v_and_b32_e32 v101, 0xffff0000, v174
	v_lshlrev_b32_e32 v98, 16, v175
	s_waitcnt lgkmcnt(0)
	v_and_b32_e32 v99, 0xffff0000, v175
	v_lshlrev_b32_e32 v104, 16, v176
	v_and_b32_e32 v105, 0xffff0000, v176
	v_pk_add_f32 v[98:99], v[96:97], v[98:99]
	v_pk_add_f32 v[102:103], v[94:95], v[100:101]
	v_pk_add_f32 v[104:105], v[90:91], v[104:105]
	v_mul_f32_e32 v90, v103, v103
	v_mul_f32_e32 v91, v99, v99
	v_fmac_f32_e32 v90, v102, v102
	v_fmac_f32_e32 v91, v98, v98
	v_lshlrev_b32_e32 v106, 16, v177
	v_and_b32_e32 v107, 0xffff0000, v177
	v_add_f32_e32 v90, v90, v91
	v_mul_f32_e32 v91, v105, v105
	v_pk_add_f32 v[100:101], v[92:93], v[106:107]
	v_fmac_f32_e32 v91, v104, v104
	v_add_f32_e32 v90, v91, v90
	v_mul_f32_e32 v91, v101, v101
	v_fmac_f32_e32 v91, v100, v100
	v_add_f32_e32 v174, v91, v90
	v_lshlrev_b32_e32 v90, 16, v170
	v_and_b32_e32 v91, 0xffff0000, v170
	v_lshlrev_b32_e32 v92, 16, v171
	v_and_b32_e32 v93, 0xffff0000, v171
	v_lshlrev_b32_e32 v94, 16, v172
	v_and_b32_e32 v95, 0xffff0000, v172
	v_pk_add_f32 v[106:107], v[88:89], v[92:93]
	v_pk_add_f32 v[110:111], v[86:87], v[90:91]
	v_pk_add_f32 v[112:113], v[82:83], v[94:95]
	v_mul_f32_e32 v82, v111, v111
	v_mul_f32_e32 v83, v107, v107
	v_fmac_f32_e32 v82, v110, v110
	v_fmac_f32_e32 v83, v106, v106
	v_lshlrev_b32_e32 v96, 16, v173
	v_and_b32_e32 v97, 0xffff0000, v173
	v_add_f32_e32 v82, v82, v83
	v_mul_f32_e32 v83, v113, v113
	v_pk_add_f32 v[108:109], v[84:85], v[96:97]
	v_fmac_f32_e32 v83, v112, v112
	v_add_f32_e32 v82, v83, v82
	v_mul_f32_e32 v83, v109, v109
	v_fmac_f32_e32 v83, v108, v108
	v_add_f32_e32 v82, v83, v82
	v_add_f32_e32 v82, v174, v82
	v_mov_b32_e32 v83, v82
	s_nop 1
	v_permlane16_swap_b32_e32 v82, v83
	s_waitcnt lgkmcnt(0)
	v_add_f32_e32 v82, v82, v83
	v_mov_b32_e32 v83, v82
	s_nop 1
	v_permlane32_swap_b32_e32 v82, v83
	s_and_saveexec_b64 s[0:1], vcc
	s_cbranch_execz .LBB0_357
	s_waitcnt lgkmcnt(0)
	v_add_f32_e32 v84, v82, v83
	v_lshlrev_b64 v[82:83], 6, v[228:229]
	v_lshl_add_u64 v[82:83], s[22:23], 0, v[82:83]
	v_lshl_add_u64 v[82:83], s[36:37], 2, v[82:83]
	s_lshl_b32 s92, s52, 2
	v_lshl_add_u64 v[82:83], v[82:83], 0, s[92:93]
	global_store_dword v[82:83], v84, off sc1
; __device__ __forceinline__ void unpack8(const u32x4 w, float (&f)[8]) { f[0] = bf_lo(w.x); f[1] = bf_hi(w.x); f[2] = bf_lo(w.y); f[3] = bf_hi(w.y); f[4] = bf_lo(w.z); f[5] = bf_hi(w.z); f[6] = bf_lo(w.w); f[7] = bf_hi(w.w); }
;     __device__ __forceinline__ void operator()(f32x4 (&acc)[2][2][4][2], const Unit& u, int wr, int wc, int fr, int fq) const {
;     ...
;             for (int m = 0; m < 4; ++m) { const int row = row0 + ai * HALF + m * 16; float sq = 0.f;
; #pragma unroll
;                 for (int bj = 0; bj < 2; ++bj) {
;                     float xf[8]; unpack8(xo[ai][m][bj], xf);
;                     const f32x4 x0 = (f32x4){xf[0], xf[1], xf[2], xf[3]} + acc[ai][bj][m][0], x1 = (f32x4){xf[4], xf[5], xf[6], xf[7]} + acc[ai][bj][m][1];
;                     sq += (x0[0] * x0[0] + x0[1] * x0[1]) + (x0[2] * x0[2] + x0[3] * x0[3]) + (x1[0] * x1[0] + x1[1] * x1[1]) + (x1[2] * x1[2] + x1[3] * x1[3]);
;                     acc[ai][bj][m][0] = x0; acc[ai][bj][m][1] = x1; }
;                 sq += __shfl_xor(sq, 16); sq += __shfl_xor(sq, 32);
;                 if (fq == 0) __hip_atomic_store(ssn + (size_t)row * 16 + u.pn * 4 + wc, sq, __ATOMIC_RELAXED, __HIP_MEMORY_SCOPE_AGENT); }
.LBB0_357:
	s_or_b64 exec, exec, s[0:1]
	v_lshlrev_b32_e32 v82, 16, v166
	s_waitcnt lgkmcnt(0)
	v_and_b32_e32 v83, 0xffff0000, v166
	v_lshlrev_b32_e32 v84, 16, v167
	v_and_b32_e32 v85, 0xffff0000, v167
	v_pk_add_f32 v[80:81], v[80:81], v[84:85]
	v_pk_add_f32 v[78:79], v[78:79], v[82:83]
	v_lshlrev_b32_e32 v86, 16, v168
	v_and_b32_e32 v87, 0xffff0000, v168
	v_mul_f32_e32 v82, v79, v79
	v_mul_f32_e32 v83, v81, v81
	v_pk_add_f32 v[74:75], v[74:75], v[86:87]
	v_fmac_f32_e32 v82, v78, v78
	v_fmac_f32_e32 v83, v80, v80
	v_lshlrev_b32_e32 v88, 16, v169
	v_and_b32_e32 v89, 0xffff0000, v169
	v_add_f32_e32 v82, v82, v83
	v_mul_f32_e32 v83, v75, v75
	v_pk_add_f32 v[76:77], v[76:77], v[88:89]
	v_fmac_f32_e32 v83, v74, v74
	v_add_f32_e32 v82, v83, v82
	v_mul_f32_e32 v83, v77, v77
	v_fmac_f32_e32 v83, v76, v76
	v_add_f32_e32 v90, v83, v82
	v_lshlrev_b32_e32 v82, 16, v162
	v_and_b32_e32 v83, 0xffff0000, v162
	v_lshlrev_b32_e32 v84, 16, v163
	v_and_b32_e32 v85, 0xffff0000, v163
	v_pk_add_f32 v[72:73], v[72:73], v[84:85]
	v_pk_add_f32 v[70:71], v[70:71], v[82:83]
	v_lshlrev_b32_e32 v86, 16, v164
	v_and_b32_e32 v87, 0xffff0000, v164
	v_mul_f32_e32 v82, v71, v71
	v_mul_f32_e32 v83, v73, v73
	v_pk_add_f32 v[66:67], v[66:67], v[86:87]
	v_fmac_f32_e32 v82, v70, v70
	v_fmac_f32_e32 v83, v72, v72
	v_lshlrev_b32_e32 v88, 16, v165
	v_and_b32_e32 v89, 0xffff0000, v165
	v_add_f32_e32 v82, v82, v83
	v_mul_f32_e32 v83, v67, v67
	v_pk_add_f32 v[68:69], v[68:69], v[88:89]
	v_fmac_f32_e32 v83, v66, v66
	v_add_f32_e32 v82, v83, v82
	v_mul_f32_e32 v83, v69, v69
	v_fmac_f32_e32 v83, v68, v68
	v_add_f32_e32 v82, v83, v82
	v_add_f32_e32 v82, v90, v82
	v_mov_b32_e32 v83, v82
	s_nop 1
	v_permlane16_swap_b32_e32 v82, v83
	s_waitcnt lgkmcnt(0)
	v_add_f32_e32 v82, v82, v83
	v_mov_b32_e32 v83, v82
	s_nop 1
	v_permlane32_swap_b32_e32 v82, v83
	s_and_saveexec_b64 s[0:1], vcc
	s_cbranch_execz .LBB0_359
	s_waitcnt lgkmcnt(0)
	v_add_f32_e32 v84, v82, v83
	v_lshlrev_b64 v[82:83], 6, v[226:227]
	v_lshl_add_u64 v[82:83], s[22:23], 0, v[82:83]
	v_lshl_add_u64 v[82:83], s[36:37], 2, v[82:83]
	s_lshl_b32 s92, s52, 2
	v_lshl_add_u64 v[82:83], v[82:83], 0, s[92:93]
	global_store_dword v[82:83], v84, off sc1
.LBB0_359:
	s_or_b64 exec, exec, s[0:1]
	v_lshlrev_b32_e32 v82, 16, v158
	s_waitcnt lgkmcnt(0)
	v_and_b32_e32 v83, 0xffff0000, v158
	v_lshlrev_b32_e32 v84, 16, v159
	v_and_b32_e32 v85, 0xffff0000, v159
	v_pk_add_f32 v[64:65], v[64:65], v[84:85]
	v_pk_add_f32 v[62:63], v[62:63], v[82:83]
	v_lshlrev_b32_e32 v86, 16, v160
	v_and_b32_e32 v87, 0xffff0000, v160
	v_mul_f32_e32 v82, v63, v63
	v_mul_f32_e32 v83, v65, v65
	v_pk_add_f32 v[58:59], v[58:59], v[86:87]
	v_fmac_f32_e32 v82, v62, v62
	v_fmac_f32_e32 v83, v64, v64
	v_lshlrev_b32_e32 v88, 16, v161
	v_and_b32_e32 v89, 0xffff0000, v161
	v_add_f32_e32 v82, v82, v83
	v_mul_f32_e32 v83, v59, v59
	v_pk_add_f32 v[60:61], v[60:61], v[88:89]
	v_fmac_f32_e32 v83, v58, v58
	v_add_f32_e32 v82, v83, v82
	v_mul_f32_e32 v83, v61, v61
	v_fmac_f32_e32 v83, v60, v60
	v_add_f32_e32 v90, v83, v82
	v_lshlrev_b32_e32 v82, 16, v154
	v_and_b32_e32 v83, 0xffff0000, v154
	v_lshlrev_b32_e32 v84, 16, v155
	v_and_b32_e32 v85, 0xffff0000, v155
	v_pk_add_f32 v[56:57], v[56:57], v[84:85]
	v_pk_add_f32 v[54:55], v[54:55], v[82:83]
	v_lshlrev_b32_e32 v86, 16, v156
	v_and_b32_e32 v87, 0xffff0000, v156
	v_mul_f32_e32 v82, v55, v55
	v_mul_f32_e32 v83, v57, v57
	v_pk_add_f32 v[50:51], v[50:51], v[86:87]
	v_fmac_f32_e32 v82, v54, v54
	v_fmac_f32_e32 v83, v56, v56
	v_lshlrev_b32_e32 v88, 16, v157
	v_and_b32_e32 v89, 0xffff0000, v157
	v_add_f32_e32 v82, v82, v83
	v_mul_f32_e32 v83, v51, v51
	v_pk_add_f32 v[52:53], v[52:53], v[88:89]
	v_fmac_f32_e32 v83, v50, v50
	v_add_f32_e32 v82, v83, v82
	v_mul_f32_e32 v83, v53, v53
	v_fmac_f32_e32 v83, v52, v52
	v_add_f32_e32 v82, v83, v82
	v_add_f32_e32 v82, v90, v82
	v_mov_b32_e32 v83, v82
	s_nop 1
	v_permlane16_swap_b32_e32 v82, v83
	s_waitcnt lgkmcnt(0)
	v_add_f32_e32 v82, v82, v83
	v_mov_b32_e32 v83, v82
	s_nop 1
	v_permlane32_swap_b32_e32 v82, v83
	s_and_saveexec_b64 s[0:1], vcc
	s_cbranch_execz .LBB0_361
	s_waitcnt lgkmcnt(0)
	v_add_f32_e32 v84, v82, v83
	v_lshlrev_b64 v[82:83], 6, v[224:225]
	v_lshl_add_u64 v[82:83], s[22:23], 0, v[82:83]
	v_lshl_add_u64 v[82:83], s[36:37], 2, v[82:83]
	s_lshl_b32 s92, s52, 2
	v_lshl_add_u64 v[82:83], v[82:83], 0, s[92:93]
	global_store_dword v[82:83], v84, off sc1
; __device__ __forceinline__ void unpack8(const u32x4 w, float (&f)[8]) { f[0] = bf_lo(w.x); f[1] = bf_hi(w.x); f[2] = bf_lo(w.y); f[3] = bf_hi(w.y); f[4] = bf_lo(w.z); f[5] = bf_hi(w.z); f[6] = bf_lo(w.w); f[7] = bf_hi(w.w); }
;     __device__ __forceinline__ void operator()(f32x4 (&acc)[2][2][4][2], const Unit& u, int wr, int wc, int fr, int fq) const {
;     ...
;             for (int m = 0; m < 4; ++m) { const int row = row0 + ai * HALF + m * 16; float sq = 0.f;
; #pragma unroll
;                 for (int bj = 0; bj < 2; ++bj) {
;                     float xf[8]; unpack8(xo[ai][m][bj], xf);
;                     const f32x4 x0 = (f32x4){xf[0], xf[1], xf[2], xf[3]} + acc[ai][bj][m][0], x1 = (f32x4){xf[4], xf[5], xf[6], xf[7]} + acc[ai][bj][m][1];
;                     sq += (x0[0] * x0[0] + x0[1] * x0[1]) + (x0[2] * x0[2] + x0[3] * x0[3]) + (x1[0] * x1[0] + x1[1] * x1[1]) + (x1[2] * x1[2] + x1[3] * x1[3]);
;                     acc[ai][bj][m][0] = x0; acc[ai][bj][m][1] = x1; }
;                 sq += __shfl_xor(sq, 16); sq += __shfl_xor(sq, 32);
;                 if (fq == 0) __hip_atomic_store(ssn + (size_t)row * 16 + u.pn * 4 + wc, sq, __ATOMIC_RELAXED, __HIP_MEMORY_SCOPE_AGENT); }
.LBB0_361:
	s_or_b64 exec, exec, s[0:1]
	v_lshlrev_b32_e32 v82, 16, v150
	s_waitcnt lgkmcnt(0)
	v_and_b32_e32 v83, 0xffff0000, v150
	v_lshlrev_b32_e32 v84, 16, v151
	v_and_b32_e32 v85, 0xffff0000, v151
	v_pk_add_f32 v[48:49], v[48:49], v[84:85]
	v_pk_add_f32 v[46:47], v[46:47], v[82:83]
	v_lshlrev_b32_e32 v86, 16, v152
	v_and_b32_e32 v87, 0xffff0000, v152
	v_mul_f32_e32 v82, v47, v47
	v_mul_f32_e32 v83, v49, v49
	v_pk_add_f32 v[42:43], v[42:43], v[86:87]
	v_fmac_f32_e32 v82, v46, v46
	v_fmac_f32_e32 v83, v48, v48
	v_lshlrev_b32_e32 v88, 16, v153
	v_and_b32_e32 v89, 0xffff0000, v153
	v_add_f32_e32 v82, v82, v83
	v_mul_f32_e32 v83, v43, v43
	v_pk_add_f32 v[44:45], v[44:45], v[88:89]
	v_fmac_f32_e32 v83, v42, v42
	v_add_f32_e32 v82, v83, v82
	v_mul_f32_e32 v83, v45, v45
	v_fmac_f32_e32 v83, v44, v44
	v_add_f32_e32 v90, v83, v82
	v_lshlrev_b32_e32 v82, 16, v142
	v_and_b32_e32 v83, 0xffff0000, v142
	v_lshlrev_b32_e32 v84, 16, v143
	v_and_b32_e32 v85, 0xffff0000, v143
	v_pk_add_f32 v[40:41], v[40:41], v[84:85]
	v_pk_add_f32 v[38:39], v[38:39], v[82:83]
	v_lshlrev_b32_e32 v86, 16, v144
	v_and_b32_e32 v87, 0xffff0000, v144
	v_mul_f32_e32 v82, v39, v39
	v_mul_f32_e32 v83, v41, v41
	v_pk_add_f32 v[34:35], v[34:35], v[86:87]
	v_fmac_f32_e32 v82, v38, v38
	v_fmac_f32_e32 v83, v40, v40
	v_lshlrev_b32_e32 v88, 16, v145
	v_and_b32_e32 v89, 0xffff0000, v145
	v_add_f32_e32 v82, v82, v83
	v_mul_f32_e32 v83, v35, v35
	v_pk_add_f32 v[36:37], v[36:37], v[88:89]
	v_fmac_f32_e32 v83, v34, v34
	v_add_f32_e32 v82, v83, v82
	v_mul_f32_e32 v83, v37, v37
	v_fmac_f32_e32 v83, v36, v36
	v_add_f32_e32 v82, v83, v82
	v_add_f32_e32 v82, v90, v82
	v_mov_b32_e32 v83, v82
	s_nop 1
	v_permlane16_swap_b32_e32 v82, v83
	s_waitcnt lgkmcnt(0)
	v_add_f32_e32 v82, v82, v83
	v_mov_b32_e32 v83, v82
	s_nop 1
	v_permlane32_swap_b32_e32 v82, v83
	s_and_saveexec_b64 s[0:1], vcc
	s_cbranch_execz .LBB0_363
	s_waitcnt lgkmcnt(0)
	v_add_f32_e32 v84, v82, v83
	v_lshlrev_b64 v[82:83], 6, v[222:223]
	v_lshl_add_u64 v[82:83], s[22:23], 0, v[82:83]
	v_lshl_add_u64 v[82:83], s[36:37], 2, v[82:83]
	s_lshl_b32 s92, s52, 2
	v_lshl_add_u64 v[82:83], v[82:83], 0, s[92:93]
	global_store_dword v[82:83], v84, off sc1
.LBB0_363:
	s_or_b64 exec, exec, s[0:1]
	v_lshlrev_b32_e32 v82, 16, v134
	s_waitcnt lgkmcnt(0)
	v_and_b32_e32 v83, 0xffff0000, v134
	v_lshlrev_b32_e32 v84, 16, v135
	v_and_b32_e32 v85, 0xffff0000, v135
	v_pk_add_f32 v[32:33], v[32:33], v[84:85]
	v_pk_add_f32 v[30:31], v[30:31], v[82:83]
	v_lshlrev_b32_e32 v86, 16, v136
	v_and_b32_e32 v87, 0xffff0000, v136
	v_mul_f32_e32 v82, v31, v31
	v_mul_f32_e32 v83, v33, v33
	v_pk_add_f32 v[26:27], v[26:27], v[86:87]
	v_fmac_f32_e32 v82, v30, v30
	v_fmac_f32_e32 v83, v32, v32
	v_lshlrev_b32_e32 v88, 16, v137
	v_and_b32_e32 v89, 0xffff0000, v137
	v_add_f32_e32 v82, v82, v83
	v_mul_f32_e32 v83, v27, v27
	v_pk_add_f32 v[28:29], v[28:29], v[88:89]
	v_fmac_f32_e32 v83, v26, v26
	v_add_f32_e32 v82, v83, v82
	v_mul_f32_e32 v83, v29, v29
	v_fmac_f32_e32 v83, v28, v28
	v_add_f32_e32 v90, v83, v82
	v_lshlrev_b32_e32 v82, 16, v130
	v_and_b32_e32 v83, 0xffff0000, v130
	v_lshlrev_b32_e32 v84, 16, v131
	v_and_b32_e32 v85, 0xffff0000, v131
	v_pk_add_f32 v[24:25], v[24:25], v[84:85]
	v_pk_add_f32 v[22:23], v[22:23], v[82:83]
	v_lshlrev_b32_e32 v86, 16, v132
	v_and_b32_e32 v87, 0xffff0000, v132
	v_mul_f32_e32 v82, v23, v23
	v_mul_f32_e32 v83, v25, v25
	v_pk_add_f32 v[18:19], v[18:19], v[86:87]
	v_fmac_f32_e32 v82, v22, v22
	v_fmac_f32_e32 v83, v24, v24
	v_lshlrev_b32_e32 v88, 16, v133
	v_and_b32_e32 v89, 0xffff0000, v133
	v_add_f32_e32 v82, v82, v83
	v_mul_f32_e32 v83, v19, v19
	v_pk_add_f32 v[20:21], v[20:21], v[88:89]
	v_fmac_f32_e32 v83, v18, v18
	v_add_f32_e32 v82, v83, v82
	v_mul_f32_e32 v83, v21, v21
	v_fmac_f32_e32 v83, v20, v20
	v_add_f32_e32 v82, v83, v82
	v_add_f32_e32 v82, v90, v82
	v_mov_b32_e32 v83, v82
	s_nop 1
	v_permlane16_swap_b32_e32 v82, v83
	s_waitcnt lgkmcnt(0)
	v_add_f32_e32 v82, v82, v83
	v_mov_b32_e32 v83, v82
	s_nop 1
	v_permlane32_swap_b32_e32 v82, v83
	s_and_saveexec_b64 s[0:1], vcc
	s_cbranch_execz .LBB0_365
	s_waitcnt lgkmcnt(0)
	v_add_f32_e32 v84, v82, v83
	v_lshlrev_b64 v[82:83], 6, v[220:221]
	v_lshl_add_u64 v[82:83], s[22:23], 0, v[82:83]
	v_lshl_add_u64 v[82:83], s[36:37], 2, v[82:83]
	s_lshl_b32 s92, s52, 2
	v_lshl_add_u64 v[82:83], v[82:83], 0, s[92:93]
	global_store_dword v[82:83], v84, off sc1
.LBB0_365:
	s_or_b64 exec, exec, s[0:1]
	v_lshlrev_b32_e32 v82, 16, v146
	s_waitcnt lgkmcnt(0)
	v_and_b32_e32 v83, 0xffff0000, v146
	v_lshlrev_b32_e32 v84, 16, v147
	v_and_b32_e32 v85, 0xffff0000, v147
	v_lshlrev_b32_e32 v86, 16, v148
	v_and_b32_e32 v87, 0xffff0000, v148
	v_pk_add_f32 v[84:85], v[16:17], v[84:85]
	v_pk_add_f32 v[88:89], v[14:15], v[82:83]
	v_pk_add_f32 v[86:87], v[10:11], v[86:87]
	v_mul_f32_e32 v10, v89, v89
	v_mul_f32_e32 v11, v85, v85
	v_fmac_f32_e32 v10, v88, v88
	v_fmac_f32_e32 v11, v84, v84
	v_lshlrev_b32_e32 v90, 16, v149
	v_and_b32_e32 v91, 0xffff0000, v149
	v_add_f32_e32 v10, v10, v11
	v_mul_f32_e32 v11, v87, v87
	v_pk_add_f32 v[82:83], v[12:13], v[90:91]
	v_fmac_f32_e32 v11, v86, v86
	v_add_f32_e32 v10, v11, v10
	v_mul_f32_e32 v11, v83, v83
	v_fmac_f32_e32 v11, v82, v82
	v_add_f32_e32 v130, v11, v10
	v_lshlrev_b32_e32 v10, 16, v138
	v_and_b32_e32 v11, 0xffff0000, v138
	v_lshlrev_b32_e32 v12, 16, v139
	v_and_b32_e32 v13, 0xffff0000, v139
	v_lshlrev_b32_e32 v14, 16, v140
	v_and_b32_e32 v15, 0xffff0000, v140
	v_pk_add_f32 v[92:93], v[8:9], v[12:13]
	v_pk_add_f32 v[96:97], v[6:7], v[10:11]
	v_pk_add_f32 v[94:95], v[2:3], v[14:15]
	v_mul_f32_e32 v2, v97, v97
	v_mul_f32_e32 v3, v93, v93
	v_fmac_f32_e32 v2, v96, v96
	v_fmac_f32_e32 v3, v92, v92
	v_lshlrev_b32_e32 v16, 16, v141
	v_and_b32_e32 v17, 0xffff0000, v141
	v_add_f32_e32 v2, v2, v3
	v_mul_f32_e32 v3, v95, v95
	v_pk_add_f32 v[90:91], v[4:5], v[16:17]
	v_fmac_f32_e32 v3, v94, v94
	v_add_f32_e32 v2, v3, v2
	v_mul_f32_e32 v3, v91, v91
	v_fmac_f32_e32 v3, v90, v90
	v_add_f32_e32 v2, v3, v2
	v_add_f32_e32 v2, v130, v2
	v_mov_b32_e32 v3, v2
	s_nop 1
	v_permlane16_swap_b32_e32 v2, v3
	s_waitcnt lgkmcnt(0)
	v_add_f32_e32 v2, v2, v3
	v_mov_b32_e32 v3, v2
	s_nop 1
	v_permlane32_swap_b32_e32 v2, v3
	s_and_saveexec_b64 s[0:1], vcc
	s_cbranch_execz .LBB0_367
	s_waitcnt lgkmcnt(0)
	v_add_f32_e32 v4, v2, v3
	v_lshlrev_b64 v[2:3], 6, v[218:219]
	v_lshl_add_u64 v[2:3], s[22:23], 0, v[2:3]
	v_lshl_add_u64 v[2:3], s[36:37], 2, v[2:3]
	s_lshl_b32 s92, s52, 2
	v_lshl_add_u64 v[2:3], v[2:3], 0, s[92:93]
	global_store_dword v[2:3], v4, off sc1

; __device__ __forceinline__ unsigned cvt_pk_bf16(float lo, float hi) { unsigned r; asm("v_cvt_pk_bf16_f32 %0, %1, %2" : "=v"(r) : "v"(lo), "v"(hi)); return r; }
;     __device__ __forceinline__ void operator()(const f32x4 (&acc)[2][2][4][2], const Unit& u, int wr, int wc, int fr, int fq) const {
;     ...
;                     sq += (v0[0] * v0[0] + v0[1] * v0[1]) + (v0[2] * v0[2] + v0[3] * v0[3]) + (v1[0] * v1[0] + v1[1] * v1[1]) + (v1[2] * v1[2] + v1[3] * v1[3]);
;                     u32x4 w; w.x = cvt_pk_bf16(v0[0], v0[1]); w.y = cvt_pk_bf16(v0[2], v0[3]); w.z = cvt_pk_bf16(v1[0], v1[1]); w.w = cvt_pk_bf16(v1[2], v1[3]);
;                     *(u32x4*)(rowp + bj * HALF) = w; }
;                 if (dss) { sq += __shfl_xor(sq, 16); sq += __shfl_xor(sq, 32); if (fq == 0) ssv[(size_t)row * 32 + (u.pn - ssv_pn0) * 4 + wc] = sq; }
.LBB0_454:
	s_cmp_gt_i32 s89, 7
	v_readlane_b32 s12, v254, 51
	s_cselect_b64 s[8:9], -1, 0
	v_readlane_b32 s13, v254, 52
	s_and_b64 s[66:67], s[12:13], s[8:9]
	v_cndmask_b32_e64 v141, 0, 1, s[66:67]
	v_cmp_gt_u32_e64 s[8:9], 16, v164
	v_cmp_ne_u32_e64 s[12:13], 1, v141
	s_andn2_b64 vcc, exec, s[66:67]
	v_cvt_pk_bf16_f32 v166, v134, v135
	v_cvt_pk_bf16_f32 v167, v136, v137
	v_cvt_pk_bf16_f32 v168, v130, v131
	v_cvt_pk_bf16_f32 v169, v132, v133
	global_store_dwordx4 v[162:163], v[166:169], off offset:256
	s_cbranch_vccnz .LBB0_458
	v_mul_f32_e32 v133, v133, v133
	v_mul_f32_e32 v131, v131, v131
	v_fmac_f32_e32 v133, v132, v132
	v_fmac_f32_e32 v131, v130, v130
	v_mul_f32_e32 v130, v135, v135
	v_mul_f32_e32 v132, v137, v137
	v_mul_f32_e32 v141, v157, v157
	v_mul_f32_e32 v145, v145, v145
	v_fmac_f32_e32 v130, v134, v134
	v_fmac_f32_e32 v132, v136, v136
	v_fmac_f32_e32 v141, v156, v156
	v_fmac_f32_e32 v145, v144, v144
	v_mul_f32_e32 v144, v159, v159
	v_add_f32_e32 v130, v130, v132
	v_add_f32_e32 v141, v141, v145
	v_fmac_f32_e32 v144, v158, v158
	v_mul_f32_e32 v143, v143, v143
	v_add_f32_e32 v130, v131, v130
	v_add_f32_e32 v141, v144, v141
	v_fmac_f32_e32 v143, v142, v142
	v_add_f32_e32 v141, v143, v141
	v_add_f32_e32 v130, v133, v130
	v_add_f32_e32 v130, v141, v130
	v_mov_b32_e32 v131, v130
	s_nop 1
	v_permlane16_swap_b32_e32 v130, v131
	s_nop 0
	s_waitcnt lgkmcnt(0)
	v_add_f32_e32 v130, v130, v131
	v_mov_b32_e32 v131, v130
	s_nop 1
	v_permlane32_swap_b32_e32 v130, v131
	s_and_saveexec_b64 s[66:67], s[8:9]
	s_cbranch_execz .LBB0_457
	v_ashrrev_i32_e32 v141, 31, v140
	s_waitcnt lgkmcnt(0)
	v_add_f32_e32 v132, v130, v131
	v_lshlrev_b64 v[130:131], 7, v[140:141]
	s_lshl_b32 s92, s89, 2
	v_lshl_add_u64 v[130:131], s[38:39], 0, v[130:131]
	v_lshl_add_u64 v[130:131], s[92:93], 2, v[130:131]
	s_lshl_b32 s92, s34, 2
	v_lshl_add_u64 v[130:131], v[130:131], 0, s[92:93]
	v_add_co_u32_e32 v130, vcc, 0xffffff80, v130
	s_nop 1
	v_addc_co_u32_e32 v131, vcc, -1, v131, vcc
	global_store_dword v[130:131], v132, off

; __device__ __forceinline__ unsigned cvt_pk_bf16(float lo, float hi) { unsigned r; asm("v_cvt_pk_bf16_f32 %0, %1, %2" : "=v"(r) : "v"(lo), "v"(hi)); return r; }
;     __device__ __forceinline__ void operator()(const f32x4 (&acc)[2][2][4][2], const Unit& u, int wr, int wc, int fr, int fq) const {
;     ...
;                     sq += (v0[0] * v0[0] + v0[1] * v0[1]) + (v0[2] * v0[2] + v0[3] * v0[3]) + (v1[0] * v1[0] + v1[1] * v1[1]) + (v1[2] * v1[2] + v1[3] * v1[3]);
;                     u32x4 w; w.x = cvt_pk_bf16(v0[0], v0[1]); w.y = cvt_pk_bf16(v0[2], v0[3]); w.z = cvt_pk_bf16(v1[0], v1[1]); w.w = cvt_pk_bf16(v1[2], v1[3]);
;                     *(u32x4*)(rowp + bj * HALF) = w; }
;                 if (dss) { sq += __shfl_xor(sq, 16); sq += __shfl_xor(sq, 32); if (fq == 0) ssv[(size_t)row * 32 + (u.pn - ssv_pn0) * 4 + wc] = sq; }
.LBB0_465:
	s_and_b64 vcc, exec, s[12:13]
	v_cvt_pk_bf16_f32 v142, v118, v119
	v_cvt_pk_bf16_f32 v143, v120, v121
	v_cvt_pk_bf16_f32 v144, v114, v115
	v_cvt_pk_bf16_f32 v145, v116, v117
	global_store_dwordx4 v[134:135], v[142:145], off offset:256
	s_cbranch_vccnz .LBB0_469
	v_mul_f32_e32 v127, v127, v127
	v_mul_f32_e32 v117, v117, v117
	v_mul_f32_e32 v115, v115, v115
	v_fmac_f32_e32 v127, v126, v126
	v_mul_f32_e32 v126, v129, v129
	v_fmac_f32_e32 v117, v116, v116
	v_fmac_f32_e32 v115, v114, v114
	v_mul_f32_e32 v114, v119, v119
	v_mul_f32_e32 v116, v121, v121
	v_fmac_f32_e32 v126, v128, v128
	v_mul_f32_e32 v123, v123, v123
	v_fmac_f32_e32 v114, v118, v118
	v_fmac_f32_e32 v116, v120, v120
	v_add_f32_e32 v126, v127, v126
	v_fmac_f32_e32 v123, v122, v122
	v_add_f32_e32 v114, v114, v116
	v_add_f32_e32 v122, v123, v126
	v_mul_f32_e32 v123, v125, v125
	v_add_f32_e32 v114, v115, v114
	v_fmac_f32_e32 v123, v124, v124
	v_add_f32_e32 v122, v123, v122
	v_add_f32_e32 v114, v117, v114
	v_add_f32_e32 v114, v122, v114
	v_mov_b32_e32 v115, v114
	s_nop 1
	v_permlane16_swap_b32_e32 v114, v115
	s_nop 0
	s_waitcnt lgkmcnt(0)
	v_add_f32_e32 v114, v114, v115
	v_mov_b32_e32 v115, v114
	s_nop 1
	v_permlane32_swap_b32_e32 v114, v115
	s_and_saveexec_b64 s[66:67], s[8:9]
	s_cbranch_execz .LBB0_468
	v_ashrrev_i32_e32 v131, 31, v130
	s_waitcnt lgkmcnt(0)
	v_add_f32_e32 v116, v114, v115
	v_lshlrev_b64 v[114:115], 7, v[130:131]
	s_lshl_b32 s92, s89, 2
	v_lshl_add_u64 v[114:115], s[38:39], 0, v[114:115]
	v_lshl_add_u64 v[114:115], s[92:93], 2, v[114:115]
	s_lshl_b32 s92, s34, 2
	v_lshl_add_u64 v[114:115], v[114:115], 0, s[92:93]
	v_add_co_u32_e32 v114, vcc, 0xffffff80, v114
	s_nop 1
	v_addc_co_u32_e32 v115, vcc, -1, v115, vcc
	global_store_dword v[114:115], v116, off

; __device__ __forceinline__ unsigned cvt_pk_bf16(float lo, float hi) { unsigned r; asm("v_cvt_pk_bf16_f32 %0, %1, %2" : "=v"(r) : "v"(lo), "v"(hi)); return r; }
;     __device__ __forceinline__ void operator()(const f32x4 (&acc)[2][2][4][2], const Unit& u, int wr, int wc, int fr, int fq) const {
;     ...
;                     sq += (v0[0] * v0[0] + v0[1] * v0[1]) + (v0[2] * v0[2] + v0[3] * v0[3]) + (v1[0] * v1[0] + v1[1] * v1[1]) + (v1[2] * v1[2] + v1[3] * v1[3]);
;                     u32x4 w; w.x = cvt_pk_bf16(v0[0], v0[1]); w.y = cvt_pk_bf16(v0[2], v0[3]); w.z = cvt_pk_bf16(v1[0], v1[1]); w.w = cvt_pk_bf16(v1[2], v1[3]);
;                     *(u32x4*)(rowp + bj * HALF) = w; }
;                 if (dss) { sq += __shfl_xor(sq, 16); sq += __shfl_xor(sq, 32); if (fq == 0) ssv[(size_t)row * 32 + (u.pn - ssv_pn0) * 4 + wc] = sq; }
.LBB0_476:
	s_and_b64 vcc, exec, s[12:13]
	v_cvt_pk_bf16_f32 v120, v102, v103
	v_cvt_pk_bf16_f32 v121, v104, v105
	v_cvt_pk_bf16_f32 v122, v98, v99
	v_cvt_pk_bf16_f32 v123, v100, v101
	global_store_dwordx4 v[118:119], v[120:123], off offset:256
	s_cbranch_vccnz .LBB0_480
	v_mul_f32_e32 v111, v111, v111
	v_mul_f32_e32 v101, v101, v101
	v_mul_f32_e32 v99, v99, v99
	v_fmac_f32_e32 v111, v110, v110
	v_mul_f32_e32 v110, v113, v113
	v_fmac_f32_e32 v101, v100, v100
	v_fmac_f32_e32 v99, v98, v98
	v_mul_f32_e32 v98, v103, v103
	v_mul_f32_e32 v100, v105, v105
	v_fmac_f32_e32 v110, v112, v112
	v_mul_f32_e32 v107, v107, v107
	v_fmac_f32_e32 v98, v102, v102
	v_fmac_f32_e32 v100, v104, v104
	v_add_f32_e32 v110, v111, v110
	v_fmac_f32_e32 v107, v106, v106
	v_add_f32_e32 v98, v98, v100
	v_add_f32_e32 v106, v107, v110
	v_mul_f32_e32 v107, v109, v109
	v_add_f32_e32 v98, v99, v98
	v_fmac_f32_e32 v107, v108, v108
	v_add_f32_e32 v106, v107, v106
	v_add_f32_e32 v98, v101, v98
	v_add_f32_e32 v98, v106, v98
	v_mov_b32_e32 v99, v98
	s_nop 1
	v_permlane16_swap_b32_e32 v98, v99
	s_nop 0
	s_waitcnt lgkmcnt(0)
	v_add_f32_e32 v98, v98, v99
	v_mov_b32_e32 v99, v98
	s_nop 1
	v_permlane32_swap_b32_e32 v98, v99
	s_and_saveexec_b64 s[66:67], s[8:9]
	s_cbranch_execz .LBB0_479
	v_ashrrev_i32_e32 v115, 31, v114
	s_waitcnt lgkmcnt(0)
	v_add_f32_e32 v100, v98, v99
	v_lshlrev_b64 v[98:99], 7, v[114:115]
	s_lshl_b32 s92, s89, 2
	v_lshl_add_u64 v[98:99], s[38:39], 0, v[98:99]
	v_lshl_add_u64 v[98:99], s[92:93], 2, v[98:99]
	s_lshl_b32 s92, s34, 2
	v_lshl_add_u64 v[98:99], v[98:99], 0, s[92:93]
	v_add_co_u32_e32 v98, vcc, 0xffffff80, v98
	s_nop 1
	v_addc_co_u32_e32 v99, vcc, -1, v99, vcc
	global_store_dword v[98:99], v100, off

; __device__ __forceinline__ unsigned cvt_pk_bf16(float lo, float hi) { unsigned r; asm("v_cvt_pk_bf16_f32 %0, %1, %2" : "=v"(r) : "v"(lo), "v"(hi)); return r; }
;     __device__ __forceinline__ void operator()(const f32x4 (&acc)[2][2][4][2], const Unit& u, int wr, int wc, int fr, int fq) const {
;     ...
;                     sq += (v0[0] * v0[0] + v0[1] * v0[1]) + (v0[2] * v0[2] + v0[3] * v0[3]) + (v1[0] * v1[0] + v1[1] * v1[1]) + (v1[2] * v1[2] + v1[3] * v1[3]);
;                     u32x4 w; w.x = cvt_pk_bf16(v0[0], v0[1]); w.y = cvt_pk_bf16(v0[2], v0[3]); w.z = cvt_pk_bf16(v1[0], v1[1]); w.w = cvt_pk_bf16(v1[2], v1[3]);
;                     *(u32x4*)(rowp + bj * HALF) = w; }
;                 if (dss) { sq += __shfl_xor(sq, 16); sq += __shfl_xor(sq, 32); if (fq == 0) ssv[(size_t)row * 32 + (u.pn - ssv_pn0) * 4 + wc] = sq; }
.LBB0_487:
	s_and_b64 vcc, exec, s[12:13]
	v_cvt_pk_bf16_f32 v104, v86, v87
	v_cvt_pk_bf16_f32 v105, v88, v89
	v_cvt_pk_bf16_f32 v106, v82, v83
	v_cvt_pk_bf16_f32 v107, v84, v85
	global_store_dwordx4 v[102:103], v[104:107], off offset:256
	s_cbranch_vccnz .LBB0_491
	v_mul_f32_e32 v95, v95, v95
	v_mul_f32_e32 v85, v85, v85
	v_mul_f32_e32 v83, v83, v83
	v_fmac_f32_e32 v95, v94, v94
	v_mul_f32_e32 v94, v97, v97
	v_fmac_f32_e32 v85, v84, v84
	v_fmac_f32_e32 v83, v82, v82
	v_mul_f32_e32 v82, v87, v87
	v_mul_f32_e32 v84, v89, v89
	v_fmac_f32_e32 v94, v96, v96
	v_mul_f32_e32 v91, v91, v91
	v_fmac_f32_e32 v82, v86, v86
	v_fmac_f32_e32 v84, v88, v88
	v_add_f32_e32 v94, v95, v94
	v_fmac_f32_e32 v91, v90, v90
	v_add_f32_e32 v82, v82, v84
	v_add_f32_e32 v90, v91, v94
	v_mul_f32_e32 v91, v93, v93
	v_add_f32_e32 v82, v83, v82
	v_fmac_f32_e32 v91, v92, v92
	v_add_f32_e32 v90, v91, v90
	v_add_f32_e32 v82, v85, v82
	v_add_f32_e32 v82, v90, v82
	v_mov_b32_e32 v83, v82
	s_nop 1
	v_permlane16_swap_b32_e32 v82, v83
	s_nop 0
	s_waitcnt lgkmcnt(0)
	v_add_f32_e32 v82, v82, v83
	v_mov_b32_e32 v83, v82
	s_nop 1
	v_permlane32_swap_b32_e32 v82, v83
	s_and_saveexec_b64 s[66:67], s[8:9]
	s_cbranch_execz .LBB0_490
	v_ashrrev_i32_e32 v99, 31, v98
	s_waitcnt lgkmcnt(0)
	v_add_f32_e32 v84, v82, v83
	v_lshlrev_b64 v[82:83], 7, v[98:99]
	s_lshl_b32 s92, s89, 2
	v_lshl_add_u64 v[82:83], s[38:39], 0, v[82:83]
	v_lshl_add_u64 v[82:83], s[92:93], 2, v[82:83]
	s_lshl_b32 s92, s34, 2
	v_lshl_add_u64 v[82:83], v[82:83], 0, s[92:93]
	v_add_co_u32_e32 v82, vcc, 0xffffff80, v82
	s_nop 1
	v_addc_co_u32_e32 v83, vcc, -1, v83, vcc
	global_store_dword v[82:83], v84, off

; __device__ __forceinline__ unsigned cvt_pk_bf16(float lo, float hi) { unsigned r; asm("v_cvt_pk_bf16_f32 %0, %1, %2" : "=v"(r) : "v"(lo), "v"(hi)); return r; }
;     __device__ __forceinline__ void operator()(const f32x4 (&acc)[2][2][4][2], const Unit& u, int wr, int wc, int fr, int fq) const {
;     ...
;                     sq += (v0[0] * v0[0] + v0[1] * v0[1]) + (v0[2] * v0[2] + v0[3] * v0[3]) + (v1[0] * v1[0] + v1[1] * v1[1]) + (v1[2] * v1[2] + v1[3] * v1[3]);
;                     u32x4 w; w.x = cvt_pk_bf16(v0[0], v0[1]); w.y = cvt_pk_bf16(v0[2], v0[3]); w.z = cvt_pk_bf16(v1[0], v1[1]); w.w = cvt_pk_bf16(v1[2], v1[3]);
;                     *(u32x4*)(rowp + bj * HALF) = w; }
;                 if (dss) { sq += __shfl_xor(sq, 16); sq += __shfl_xor(sq, 32); if (fq == 0) ssv[(size_t)row * 32 + (u.pn - ssv_pn0) * 4 + wc] = sq; }
.LBB0_498:
	s_and_b64 vcc, exec, s[12:13]
	v_cvt_pk_bf16_f32 v88, v54, v55
	v_cvt_pk_bf16_f32 v89, v56, v57
	v_cvt_pk_bf16_f32 v90, v50, v51
	v_cvt_pk_bf16_f32 v91, v52, v53
	global_store_dwordx4 v[86:87], v[88:91], off offset:256
	s_cbranch_vccnz .LBB0_502
	v_mul_f32_e32 v63, v63, v63
	v_mul_f32_e32 v53, v53, v53
	v_mul_f32_e32 v51, v51, v51
	v_fmac_f32_e32 v63, v62, v62
	v_mul_f32_e32 v62, v65, v65
	v_fmac_f32_e32 v53, v52, v52
	v_fmac_f32_e32 v51, v50, v50
	v_mul_f32_e32 v50, v55, v55
	v_mul_f32_e32 v52, v57, v57
	v_fmac_f32_e32 v62, v64, v64
	v_mul_f32_e32 v59, v59, v59
	v_fmac_f32_e32 v50, v54, v54
	v_fmac_f32_e32 v52, v56, v56
	v_add_f32_e32 v62, v63, v62
	v_fmac_f32_e32 v59, v58, v58
	v_add_f32_e32 v50, v50, v52
	v_add_f32_e32 v58, v59, v62
	v_mul_f32_e32 v59, v61, v61
	v_add_f32_e32 v50, v51, v50
	v_fmac_f32_e32 v59, v60, v60
	v_add_f32_e32 v58, v59, v58
	v_add_f32_e32 v50, v53, v50
	v_add_f32_e32 v50, v58, v50
	v_mov_b32_e32 v51, v50
	s_nop 1
	v_permlane16_swap_b32_e32 v50, v51
	s_nop 0
	s_waitcnt lgkmcnt(0)
	v_add_f32_e32 v50, v50, v51
	v_mov_b32_e32 v51, v50
	s_nop 1
	v_permlane32_swap_b32_e32 v50, v51
	s_and_saveexec_b64 s[66:67], s[8:9]
	s_cbranch_execz .LBB0_501
	v_ashrrev_i32_e32 v83, 31, v82
	s_waitcnt lgkmcnt(0)
	v_add_f32_e32 v52, v50, v51
	v_lshlrev_b64 v[50:51], 7, v[82:83]
	s_lshl_b32 s92, s89, 2
	v_lshl_add_u64 v[50:51], s[38:39], 0, v[50:51]
	v_lshl_add_u64 v[50:51], s[92:93], 2, v[50:51]
	s_lshl_b32 s92, s34, 2
	v_lshl_add_u64 v[50:51], v[50:51], 0, s[92:93]
	v_add_co_u32_e32 v50, vcc, 0xffffff80, v50
	s_nop 1
	v_addc_co_u32_e32 v51, vcc, -1, v51, vcc
	global_store_dword v[50:51], v52, off

; __device__ __forceinline__ unsigned cvt_pk_bf16(float lo, float hi) { unsigned r; asm("v_cvt_pk_bf16_f32 %0, %1, %2" : "=v"(r) : "v"(lo), "v"(hi)); return r; }
;     __device__ __forceinline__ void operator()(const f32x4 (&acc)[2][2][4][2], const Unit& u, int wr, int wc, int fr, int fq) const {
;     ...
;                     sq += (v0[0] * v0[0] + v0[1] * v0[1]) + (v0[2] * v0[2] + v0[3] * v0[3]) + (v1[0] * v1[0] + v1[1] * v1[1]) + (v1[2] * v1[2] + v1[3] * v1[3]);
;                     u32x4 w; w.x = cvt_pk_bf16(v0[0], v0[1]); w.y = cvt_pk_bf16(v0[2], v0[3]); w.z = cvt_pk_bf16(v1[0], v1[1]); w.w = cvt_pk_bf16(v1[2], v1[3]);
;                     *(u32x4*)(rowp + bj * HALF) = w; }
;                 if (dss) { sq += __shfl_xor(sq, 16); sq += __shfl_xor(sq, 32); if (fq == 0) ssv[(size_t)row * 32 + (u.pn - ssv_pn0) * 4 + wc] = sq; }
.LBB0_509:
	s_and_b64 vcc, exec, s[12:13]
	v_cvt_pk_bf16_f32 v56, v38, v39
	v_cvt_pk_bf16_f32 v57, v40, v41
	v_cvt_pk_bf16_f32 v58, v34, v35
	v_cvt_pk_bf16_f32 v59, v36, v37
	global_store_dwordx4 v[54:55], v[56:59], off offset:256
	s_cbranch_vccnz .LBB0_513
	v_mul_f32_e32 v47, v47, v47
	v_mul_f32_e32 v37, v37, v37
	v_mul_f32_e32 v35, v35, v35
	v_fmac_f32_e32 v47, v46, v46
	v_mul_f32_e32 v46, v49, v49
	v_fmac_f32_e32 v37, v36, v36
	v_fmac_f32_e32 v35, v34, v34
	v_mul_f32_e32 v34, v39, v39
	v_mul_f32_e32 v36, v41, v41
	v_fmac_f32_e32 v46, v48, v48
	v_mul_f32_e32 v43, v43, v43
	v_fmac_f32_e32 v34, v38, v38
	v_fmac_f32_e32 v36, v40, v40
	v_add_f32_e32 v46, v47, v46
	v_fmac_f32_e32 v43, v42, v42
	v_add_f32_e32 v34, v34, v36
	v_add_f32_e32 v42, v43, v46
	v_mul_f32_e32 v43, v45, v45
	v_add_f32_e32 v34, v35, v34
	v_fmac_f32_e32 v43, v44, v44
	v_add_f32_e32 v42, v43, v42
	v_add_f32_e32 v34, v37, v34
	v_add_f32_e32 v34, v42, v34
	v_mov_b32_e32 v35, v34
	s_nop 1
	v_permlane16_swap_b32_e32 v34, v35
	s_nop 0
	s_waitcnt lgkmcnt(0)
	v_add_f32_e32 v34, v34, v35
	v_mov_b32_e32 v35, v34
	s_nop 1
	v_permlane32_swap_b32_e32 v34, v35
	s_and_saveexec_b64 s[66:67], s[8:9]
	s_cbranch_execz .LBB0_512
	v_ashrrev_i32_e32 v51, 31, v50
	s_waitcnt lgkmcnt(0)
	v_add_f32_e32 v36, v34, v35
	v_lshlrev_b64 v[34:35], 7, v[50:51]
	s_lshl_b32 s92, s89, 2
	v_lshl_add_u64 v[34:35], s[38:39], 0, v[34:35]
	v_lshl_add_u64 v[34:35], s[92:93], 2, v[34:35]
	s_lshl_b32 s92, s34, 2
	v_lshl_add_u64 v[34:35], v[34:35], 0, s[92:93]
	v_add_co_u32_e32 v34, vcc, 0xffffff80, v34
	s_nop 1
	v_addc_co_u32_e32 v35, vcc, -1, v35, vcc
	global_store_dword v[34:35], v36, off

; __device__ __forceinline__ unsigned cvt_pk_bf16(float lo, float hi) { unsigned r; asm("v_cvt_pk_bf16_f32 %0, %1, %2" : "=v"(r) : "v"(lo), "v"(hi)); return r; }
;     __device__ __forceinline__ void operator()(const f32x4 (&acc)[2][2][4][2], const Unit& u, int wr, int wc, int fr, int fq) const {
;     ...
;                     sq += (v0[0] * v0[0] + v0[1] * v0[1]) + (v0[2] * v0[2] + v0[3] * v0[3]) + (v1[0] * v1[0] + v1[1] * v1[1]) + (v1[2] * v1[2] + v1[3] * v1[3]);
;                     u32x4 w; w.x = cvt_pk_bf16(v0[0], v0[1]); w.y = cvt_pk_bf16(v0[2], v0[3]); w.z = cvt_pk_bf16(v1[0], v1[1]); w.w = cvt_pk_bf16(v1[2], v1[3]);
;                     *(u32x4*)(rowp + bj * HALF) = w; }
;                 if (dss) { sq += __shfl_xor(sq, 16); sq += __shfl_xor(sq, 32); if (fq == 0) ssv[(size_t)row * 32 + (u.pn - ssv_pn0) * 4 + wc] = sq; }
.LBB0_520:
	s_and_b64 vcc, exec, s[12:13]
	v_cvt_pk_bf16_f32 v40, v22, v23
	v_cvt_pk_bf16_f32 v41, v24, v25
	v_cvt_pk_bf16_f32 v42, v18, v19
	v_cvt_pk_bf16_f32 v43, v20, v21
	global_store_dwordx4 v[38:39], v[40:43], off offset:256
	s_cbranch_vccnz .LBB0_524
	v_mul_f32_e32 v31, v31, v31
	v_mul_f32_e32 v21, v21, v21
	v_mul_f32_e32 v19, v19, v19
	v_fmac_f32_e32 v31, v30, v30
	v_mul_f32_e32 v30, v33, v33
	v_fmac_f32_e32 v21, v20, v20
	v_fmac_f32_e32 v19, v18, v18
	v_mul_f32_e32 v18, v23, v23
	v_mul_f32_e32 v20, v25, v25
	v_fmac_f32_e32 v30, v32, v32
	v_mul_f32_e32 v27, v27, v27
	v_fmac_f32_e32 v18, v22, v22
	v_fmac_f32_e32 v20, v24, v24
	v_add_f32_e32 v30, v31, v30
	v_fmac_f32_e32 v27, v26, v26
	v_add_f32_e32 v18, v18, v20
	v_add_f32_e32 v26, v27, v30
	v_mul_f32_e32 v27, v29, v29
	v_add_f32_e32 v18, v19, v18
	v_fmac_f32_e32 v27, v28, v28
	v_add_f32_e32 v26, v27, v26
	v_add_f32_e32 v18, v21, v18
	v_add_f32_e32 v18, v26, v18
	v_mov_b32_e32 v19, v18
	s_nop 1
	v_permlane16_swap_b32_e32 v18, v19
	s_nop 0
	s_waitcnt lgkmcnt(0)
	v_add_f32_e32 v18, v18, v19
	v_mov_b32_e32 v19, v18
	s_nop 1
	v_permlane32_swap_b32_e32 v18, v19
	s_and_saveexec_b64 s[66:67], s[8:9]
	s_cbranch_execz .LBB0_523
	v_ashrrev_i32_e32 v35, 31, v34
	s_waitcnt lgkmcnt(0)
	v_add_f32_e32 v20, v18, v19
	v_lshlrev_b64 v[18:19], 7, v[34:35]
	s_lshl_b32 s92, s89, 2
	v_lshl_add_u64 v[18:19], s[38:39], 0, v[18:19]
	v_lshl_add_u64 v[18:19], s[92:93], 2, v[18:19]
	s_lshl_b32 s92, s34, 2
	v_lshl_add_u64 v[18:19], v[18:19], 0, s[92:93]
	v_add_co_u32_e32 v18, vcc, 0xffffff80, v18
	s_nop 1
	v_addc_co_u32_e32 v19, vcc, -1, v19, vcc
	global_store_dword v[18:19], v20, off

; __device__ __forceinline__ unsigned cvt_pk_bf16(float lo, float hi) { unsigned r; asm("v_cvt_pk_bf16_f32 %0, %1, %2" : "=v"(r) : "v"(lo), "v"(hi)); return r; }
;     __device__ __forceinline__ void operator()(const f32x4 (&acc)[2][2][4][2], const Unit& u, int wr, int wc, int fr, int fq) const {
;     ...
;                 for (int bj = 0; bj < 2; ++bj) { f32x4 v0 = acc[ai][bj][m][0] * rs + bv[bj][0], v1 = acc[ai][bj][m][1] * rs + bv[bj][1];
;                     if (act) { const f32x2v a = gelu_tanh_pk((f32x2v){v0[0], v0[1]}), b = gelu_tanh_pk((f32x2v){v0[2], v0[3]}), c = gelu_tanh_pk((f32x2v){v1[0], v1[1]}), d = gelu_tanh_pk((f32x2v){v1[2], v1[3]});
;                         v0 = (f32x4){a.x, a.y, b.x, b.y}; v1 = (f32x4){c.x, c.y, d.x, d.y}; }
;                     sq += (v0[0] * v0[0] + v0[1] * v0[1]) + (v0[2] * v0[2] + v0[3] * v0[3]) + (v1[0] * v1[0] + v1[1] * v1[1]) + (v1[2] * v1[2] + v1[3] * v1[3]);
;                     u32x4 w; w.x = cvt_pk_bf16(v0[0], v0[1]); w.y = cvt_pk_bf16(v0[2], v0[3]); w.z = cvt_pk_bf16(v1[0], v1[1]); w.w = cvt_pk_bf16(v1[2], v1[3]);
;                     *(u32x4*)(rowp + bj * HALF) = w; }
;                 if (dss) { sq += __shfl_xor(sq, 16); sq += __shfl_xor(sq, 32); if (fq == 0) ssv[(size_t)row * 32 + (u.pn - ssv_pn0) * 4 + wc] = sq; }
.LBB0_531:
	s_and_b64 vcc, exec, s[12:13]
	v_cvt_pk_bf16_f32 v24, v6, v7
	v_cvt_pk_bf16_f32 v25, v8, v9
	v_cvt_pk_bf16_f32 v26, v2, v3
	v_cvt_pk_bf16_f32 v27, v4, v5
	global_store_dwordx4 v[22:23], v[24:27], off offset:256
	s_cbranch_vccnz .LBB0_535
	v_mul_f32_e32 v15, v15, v15
	v_mul_f32_e32 v5, v5, v5
	v_mul_f32_e32 v3, v3, v3
	v_fmac_f32_e32 v15, v14, v14
	v_mul_f32_e32 v14, v17, v17
	v_fmac_f32_e32 v5, v4, v4
	v_fmac_f32_e32 v3, v2, v2
	v_mul_f32_e32 v2, v7, v7
	v_mul_f32_e32 v4, v9, v9
	v_fmac_f32_e32 v14, v16, v16
	v_mul_f32_e32 v11, v11, v11
	v_fmac_f32_e32 v2, v6, v6
	v_fmac_f32_e32 v4, v8, v8
	v_add_f32_e32 v14, v15, v14
	v_fmac_f32_e32 v11, v10, v10
	v_add_f32_e32 v2, v2, v4
	v_add_f32_e32 v10, v11, v14
	v_mul_f32_e32 v11, v13, v13
	v_add_f32_e32 v2, v3, v2
	v_fmac_f32_e32 v11, v12, v12
	v_add_f32_e32 v10, v11, v10
	v_add_f32_e32 v2, v5, v2
	v_add_f32_e32 v2, v10, v2
	v_mov_b32_e32 v3, v2
	s_nop 1
	v_permlane16_swap_b32_e32 v2, v3
	s_nop 0
	s_waitcnt lgkmcnt(0)
	v_add_f32_e32 v2, v2, v3
	v_mov_b32_e32 v3, v2
	s_nop 1
	v_permlane32_swap_b32_e32 v2, v3
	s_and_saveexec_b64 s[6:7], s[8:9]
	s_cbranch_execz .LBB0_534
	v_ashrrev_i32_e32 v19, 31, v18
	s_waitcnt lgkmcnt(0)
	v_add_f32_e32 v4, v2, v3
	v_lshlrev_b64 v[2:3], 7, v[18:19]
	s_lshl_b32 s92, s89, 2
	v_lshl_add_u64 v[2:3], s[38:39], 0, v[2:3]
	v_lshl_add_u64 v[2:3], s[92:93], 2, v[2:3]
	s_lshl_b32 s92, s34, 2
	v_lshl_add_u64 v[2:3], v[2:3], 0, s[92:93]
	v_add_co_u32_e32 v2, vcc, 0xffffff80, v2
	s_nop 1
	v_addc_co_u32_e32 v3, vcc, -1, v3, vcc
	global_store_dword v[2:3], v4, off
